# S5 helper: bu tiles transposed to the scan layout inside the wave with v_permlane32_swap/16_swap (no LDS round trip: 16 LDS writes and 16 LDS reads per chunk removed)
# speedup vs baseline: 1.0154x; 1.0154x over previous
.LBB0_398:
	s_or_b64 exec, exec, s[38:39]
	v_lshl_or_b32 v2, s8, 10, v142
	v_mov_b32_e32 v3, v0
	v_lshl_add_u64 v[2:3], v[68:69], 0, v[2:3]
	global_load_ushort v212, v[2:3], off
	global_load_ushort v213, v[2:3], off offset:1024
	global_load_ushort v214, v[2:3], off offset:2048
	global_load_ushort v215, v[2:3], off offset:3072
	v_add_u32_e32 v91, v143, v102
	ds_read_b128 v[92:95], v91 offset:12544
	ds_read_b128 v[164:167], v91 offset:13056
	ds_read_b128 v[216:219], v91 offset:13568
	ds_read_b128 v[220:223], v146 offset:12544
	ds_read_b128 v[224:227], v91 offset:14592
	ds_read_b128 v[228:231], v91 offset:15104
	ds_read_b128 v[244:247], v91 offset:15616
	ds_read_b128 v[248:251], v147 offset:12544
	s_andn2_b64 vcc, exec, s[50:51]
	s_waitcnt lgkmcnt(7)
	v_mfma_f32_16x16x32_bf16 v[92:95], v[12:15], v[92:95], 0
	s_waitcnt lgkmcnt(6)
	v_mfma_f32_16x16x32_bf16 v[164:167], v[12:15], v[164:167], 0
	s_waitcnt lgkmcnt(5)
	v_mfma_f32_16x16x32_bf16 v[216:219], v[12:15], v[216:219], 0
	s_waitcnt lgkmcnt(4)
	v_mfma_f32_16x16x32_bf16 v[220:223], v[12:15], v[220:223], 0
	s_waitcnt lgkmcnt(3)
	v_mfma_f32_16x16x32_bf16 v[224:227], v[12:15], v[224:227], 0
	s_waitcnt lgkmcnt(2)
	v_mfma_f32_16x16x32_bf16 v[228:231], v[12:15], v[228:231], 0
	s_waitcnt lgkmcnt(1)
	v_mfma_f32_16x16x32_bf16 v[244:247], v[12:15], v[244:247], 0
	s_waitcnt lgkmcnt(0)
	v_mfma_f32_16x16x32_bf16 v[248:251], v[12:15], v[248:251], 0
	s_nop 1
	v_permlane32_swap_b32_e32 v92, v216
	v_permlane32_swap_b32_e32 v164, v220
	v_permlane32_swap_b32_e32 v93, v217
	v_permlane32_swap_b32_e32 v165, v221
	v_permlane32_swap_b32_e32 v94, v218
	v_permlane32_swap_b32_e32 v166, v222
	v_permlane32_swap_b32_e32 v95, v219
	v_permlane32_swap_b32_e32 v167, v223
	v_permlane16_swap_b32_e32 v92, v164
	v_permlane16_swap_b32_e32 v216, v220
	v_permlane16_swap_b32_e32 v93, v165
	v_permlane16_swap_b32_e32 v217, v221
	v_permlane16_swap_b32_e32 v94, v166
	v_permlane16_swap_b32_e32 v218, v222
	v_permlane16_swap_b32_e32 v95, v167
	v_permlane16_swap_b32_e32 v219, v223
	v_permlane32_swap_b32_e32 v224, v244
	v_permlane32_swap_b32_e32 v228, v248
	v_permlane32_swap_b32_e32 v225, v245
	v_permlane32_swap_b32_e32 v229, v249
	v_permlane32_swap_b32_e32 v226, v246
	v_permlane32_swap_b32_e32 v230, v250
	v_permlane32_swap_b32_e32 v227, v247
	v_permlane32_swap_b32_e32 v231, v251
	v_permlane16_swap_b32_e32 v224, v228
	v_permlane16_swap_b32_e32 v244, v248
	v_permlane16_swap_b32_e32 v225, v229
	v_permlane16_swap_b32_e32 v245, v249
	v_permlane16_swap_b32_e32 v226, v230
	v_permlane16_swap_b32_e32 v246, v250
	v_permlane16_swap_b32_e32 v227, v231
	v_permlane16_swap_b32_e32 v247, v251
	s_waitcnt lgkmcnt(0)
	v_lshl_add_u32 v91, v98, 1, v141
	v_fma_f32 v14, -v64, v61, v92
	v_fma_f32 v15, v64, v60, v224
	v_pk_fma_f32 v[60:61], v[56:57], v[60:61], v[14:15] op_sel_hi:[0,1,1]
	v_cvt_pk_bf16_f32 v12, v60, v61
	ds_write_b32 v91, v12 offset:8192
	v_fma_f32 v14, -v64, v61, v93
	v_fma_f32 v15, v64, v60, v225
	v_pk_fma_f32 v[60:61], v[56:57], v[60:61], v[14:15] op_sel_hi:[0,1,1]
	v_cvt_pk_bf16_f32 v13, v60, v61
	ds_write_b32 v91, v13 offset:8464
	v_fma_f32 v14, -v64, v61, v94
	v_fma_f32 v15, v64, v60, v226
	v_pk_fma_f32 v[60:61], v[56:57], v[60:61], v[14:15] op_sel_hi:[0,1,1]
	v_cvt_pk_bf16_f32 v12, v60, v61
	ds_write_b32 v91, v12 offset:8736
	v_fma_f32 v14, -v64, v61, v95
	v_fma_f32 v15, v64, v60, v227
	v_pk_fma_f32 v[60:61], v[56:57], v[60:61], v[14:15] op_sel_hi:[0,1,1]
	v_cvt_pk_bf16_f32 v13, v60, v61
	ds_write_b32 v91, v13 offset:9008
	v_fma_f32 v14, -v64, v61, v164
	v_fma_f32 v15, v64, v60, v228
	v_pk_fma_f32 v[60:61], v[56:57], v[60:61], v[14:15] op_sel_hi:[0,1,1]
	v_cvt_pk_bf16_f32 v12, v60, v61
	ds_write_b32 v91, v12 offset:9280
	v_fma_f32 v14, -v64, v61, v165
	v_fma_f32 v15, v64, v60, v229
	v_pk_fma_f32 v[60:61], v[56:57], v[60:61], v[14:15] op_sel_hi:[0,1,1]
	v_cvt_pk_bf16_f32 v13, v60, v61
	ds_write_b32 v91, v13 offset:9552
	v_fma_f32 v14, -v64, v61, v166
	v_fma_f32 v15, v64, v60, v230
	v_pk_fma_f32 v[60:61], v[56:57], v[60:61], v[14:15] op_sel_hi:[0,1,1]
	v_cvt_pk_bf16_f32 v12, v60, v61
	ds_write_b32 v91, v12 offset:9824
	v_fma_f32 v14, -v64, v61, v167
	v_fma_f32 v15, v64, v60, v231
	v_pk_fma_f32 v[60:61], v[56:57], v[60:61], v[14:15] op_sel_hi:[0,1,1]
	v_cvt_pk_bf16_f32 v13, v60, v61
	ds_write_b32 v91, v13 offset:10096
	v_fma_f32 v14, -v64, v61, v216
	v_fma_f32 v15, v64, v60, v244
	v_pk_fma_f32 v[60:61], v[56:57], v[60:61], v[14:15] op_sel_hi:[0,1,1]
	v_cvt_pk_bf16_f32 v12, v60, v61
	ds_write_b32 v91, v12 offset:10368
	v_fma_f32 v14, -v64, v61, v217
	v_fma_f32 v15, v64, v60, v245
	v_pk_fma_f32 v[60:61], v[56:57], v[60:61], v[14:15] op_sel_hi:[0,1,1]
	v_cvt_pk_bf16_f32 v13, v60, v61
	ds_write_b32 v91, v13 offset:10640
	v_fma_f32 v14, -v64, v61, v218
	v_fma_f32 v15, v64, v60, v246
	v_pk_fma_f32 v[60:61], v[56:57], v[60:61], v[14:15] op_sel_hi:[0,1,1]
	v_cvt_pk_bf16_f32 v12, v60, v61
	ds_write_b32 v91, v12 offset:10912
	v_fma_f32 v14, -v64, v61, v219
	v_fma_f32 v15, v64, v60, v247
	v_pk_fma_f32 v[60:61], v[56:57], v[60:61], v[14:15] op_sel_hi:[0,1,1]
	v_cvt_pk_bf16_f32 v13, v60, v61
	ds_write_b32 v91, v13 offset:11184
	v_fma_f32 v14, -v64, v61, v220
	v_fma_f32 v15, v64, v60, v248
	v_pk_fma_f32 v[60:61], v[56:57], v[60:61], v[14:15] op_sel_hi:[0,1,1]
	v_cvt_pk_bf16_f32 v12, v60, v61
	ds_write_b32 v91, v12 offset:11456
	v_fma_f32 v14, -v64, v61, v221
	v_fma_f32 v15, v64, v60, v249
	v_pk_fma_f32 v[60:61], v[56:57], v[60:61], v[14:15] op_sel_hi:[0,1,1]
	v_cvt_pk_bf16_f32 v13, v60, v61
	ds_write_b32 v91, v13 offset:11728
	v_fma_f32 v14, -v64, v61, v222
	v_fma_f32 v15, v64, v60, v250
	v_pk_fma_f32 v[60:61], v[56:57], v[60:61], v[14:15] op_sel_hi:[0,1,1]
	v_cvt_pk_bf16_f32 v12, v60, v61
	ds_write_b32 v91, v12 offset:12000
	v_fma_f32 v14, -v64, v61, v223
	v_fma_f32 v15, v64, v60, v251
	v_pk_fma_f32 v[60:61], v[56:57], v[60:61], v[14:15] op_sel_hi:[0,1,1]
	v_cvt_pk_bf16_f32 v13, v60, v61
	ds_write_b32 v91, v13 offset:12272
	s_waitcnt lgkmcnt(0)
	ds_read_b128 v[12:15], v144 offset:8192
	ds_read_b128 v[92:95], v145 offset:16640
	ds_read_b128 v[216:219], v144 offset:8256
	ds_read_b128 v[220:223], v145 offset:16704
	ds_read_b128 v[224:227], v144 offset:8320
	ds_read_b128 v[228:231], v145 offset:16768
	ds_read_b128 v[244:247], v144 offset:8384
	ds_read_b128 v[248:251], v145 offset:16832
	s_waitcnt lgkmcnt(6)
	v_mfma_f32_16x16x32_bf16 v[12:15], v[12:15], v[92:95], 0
	s_waitcnt lgkmcnt(4)
	v_mfma_f32_16x16x32_bf16 v[12:15], v[216:219], v[220:223], v[12:15]
	s_waitcnt lgkmcnt(2)
	v_mfma_f32_16x16x32_bf16 v[12:15], v[224:227], v[228:231], v[12:15]
	s_waitcnt lgkmcnt(0)
	v_mfma_f32_16x16x32_bf16 v[12:15], v[244:247], v[248:251], v[12:15]
	s_nop 7
	s_waitcnt vmcnt(0)
	v_lshlrev_b32_e32 v88, 16, v212
	v_lshlrev_b32_e32 v89, 16, v213
	v_lshlrev_b32_e32 v90, 16, v214
	v_lshlrev_b32_e32 v91, 16, v215
	v_pk_fma_f32 v[12:13], v[148:149], v[88:89], v[12:13] op_sel_hi:[0,1,1]
	v_pk_fma_f32 v[14:15], v[148:149], v[90:91], v[14:15] op_sel_hi:[0,1,1]
	v_mov_b32_e32 v88, 0x3dd2d3e8
	v_mov_b32_e32 v90, 0x40135761
	v_pk_mul_f32 v[92:93], v[12:13], v[12:13]
	v_pk_mul_f32 v[94:95], v[14:15], v[14:15]
	v_pk_fma_f32 v[92:93], v[92:93], v[88:89], v[90:91] op_sel_hi:[1,0,0]
	v_pk_fma_f32 v[94:95], v[94:95], v[88:89], v[90:91] op_sel_hi:[1,0,0]
	v_pk_mul_f32 v[92:93], v[92:93], v[12:13]
	v_pk_mul_f32 v[94:95], v[94:95], v[14:15]
	v_mov_b32_e32 v88, 1.0
	v_exp_f32_e32 v92, v92
	v_exp_f32_e32 v93, v93
	v_exp_f32_e32 v94, v94
	v_exp_f32_e32 v95, v95
	s_nop 0
	v_pk_add_f32 v[92:93], v[92:93], v[88:89] op_sel_hi:[1,0]
	v_pk_add_f32 v[94:95], v[94:95], v[88:89] op_sel_hi:[1,0]
	v_rcp_f32_e32 v92, v92
	v_rcp_f32_e32 v93, v93
	v_rcp_f32_e32 v94, v94
	v_rcp_f32_e32 v95, v95
	s_nop 0
	v_pk_fma_f32 v[12:13], v[12:13], v[92:93], v[12:13] neg_lo:[1,0,0] neg_hi:[1,0,0]
	v_pk_fma_f32 v[14:15], v[14:15], v[94:95], v[14:15] neg_lo:[1,0,0] neg_hi:[1,0,0]
	v_cvt_pk_bf16_f32 v12, v12, v13
	v_cvt_pk_bf16_f32 v14, v14, v15
	global_store_short v[2:3], v12, off
	global_store_short_d16_hi v[2:3], v12, off offset:1024
	global_store_short v[2:3], v14, off offset:2048
	global_store_short_d16_hi v[2:3], v14, off offset:3072
	s_waitcnt lgkmcnt(0)
	v_lshlrev_b32_e32 v1, 2, v128
	s_cbranch_vccnz .LBB0_408
	s_waitcnt vmcnt(4)
	v_lshlrev_b32_e32 v16, 16, v176
	v_lshlrev_b32_e32 v30, 16, v177
	v_lshlrev_b32_e32 v32, 16, v178
	v_lshlrev_b32_e32 v36, 16, v179
	v_lshlrev_b32_e32 v17, 16, v180
	v_lshlrev_b32_e32 v26, 16, v181
	v_lshlrev_b32_e32 v27, 16, v182
	v_lshlrev_b32_e32 v28, 16, v183
	v_lshlrev_b32_e32 v29, 16, v184
	v_lshlrev_b32_e32 v31, 16, v185
	v_lshlrev_b32_e32 v33, 16, v186
	v_lshlrev_b32_e32 v37, 16, v187
	v_lshlrev_b32_e32 v34, 16, v188
	v_lshlrev_b32_e32 v35, 16, v189
	v_lshlrev_b32_e32 v38, 16, v190
	v_lshlrev_b32_e32 v39, 16, v195
	v_lshlrev_b32_e32 v40, 16, v197
	v_lshlrev_b32_e32 v43, 16, v198
	v_lshlrev_b32_e32 v42, 16, v199
	v_lshlrev_b32_e32 v45, 16, v200
	v_lshlrev_b32_e32 v44, 16, v201
	v_lshlrev_b32_e32 v46, 16, v203
	v_lshlrev_b32_e32 v49, 16, v204
	v_lshlrev_b32_e32 v48, 16, v205
	v_lshlrev_b32_e32 v41, 16, v196
	v_lshlrev_b32_e32 v47, 16, v202
	v_lshlrev_b32_e32 v51, 16, v206
	v_lshlrev_b32_e32 v50, 16, v207
	v_lshlrev_b32_e32 v53, 16, v191
	v_lshlrev_b32_e32 v52, 16, v193
	v_lshlrev_b32_e32 v55, 16, v192
	v_lshlrev_b32_e32 v54, 16, v194
	v_add_f32_e32 v88, v155, v35
	v_mul_f32_e32 v88, 0xbfb8aa3b, v88
	v_exp_f32_e32 v88, v88
	v_pk_add_f32 v[12:13], v[32:33], v[26:27] neg_lo:[0,1] neg_hi:[0,1]
	v_pk_add_f32 v[2:3], v[30:31], v[16:17] neg_lo:[0,1] neg_hi:[0,1]
	v_fma_f32 v13, v150, v13, v27
	v_add_f32_e32 v88, 1.0, v88
	v_rcp_f32_e32 v88, v88
	v_mul_f32_e32 v92, v157, v13
	v_fma_f32 v3, v149, v3, v17
	s_bitcmp1_b32 s3, 0
	v_mul_f32_e32 v89, 0xbf6002b1, v88
	v_cmp_gt_f32_e32 vcc, s85, v89
	s_cselect_b32 s8, 0x5000, 0
	v_mov_b32_e32 v94, v0
	v_cndmask_b32_e32 v89, 0, v239, vcc
	v_fmac_f32_e32 v89, 0xbf6002b1, v88
	v_exp_f32_e32 v88, v89
	v_cndmask_b32_e32 v89, 0, v236, vcc
	s_add_i32 s9, s8, 0
	s_mul_i32 s8, s3, 0xab
	v_ldexp_f32 v90, v88, v89
	v_add_f32_e32 v88, v154, v39
	v_mul_f32_e32 v88, 0xbfb8aa3b, v88
	v_exp_f32_e32 v88, v88
	v_mov_b32_e32 v89, v0
	s_bfe_u32 s8, s8, 0x70009
	s_mul_i32 s8, s8, 3
	v_add_f32_e32 v88, 1.0, v88
	v_rcp_f32_e32 v91, v88
	v_mul_f32_e32 v88, v92, v92
	s_sub_i32 s8, s3, s8
	s_and_b32 s8, s8, 0xff
	v_mov_b32_dpp v89, v88 quad_perm:[1,0,3,2] row_mask:0xf bank_mask:0xf
	v_fmac_f32_e32 v89, v92, v92
	s_mulk_i32 s8, 0x1100
	s_add_i32 s8, s8, 0
	v_add_f32_dpp v88, v89, v89 quad_perm:[2,3,0,1] row_mask:0xf bank_mask:0xf bound_ctrl:1
	v_pk_add_f32 v[14:15], v[36:37], v[28:29] neg_lo:[0,1] neg_hi:[0,1]
	s_nop 0
	v_add_f32_dpp v88, v88, v88 row_half_mirror row_mask:0xf bank_mask:0xf bound_ctrl:1
	v_fma_f32 v15, v151, v15, v29
	s_nop 0
	v_add_f32_dpp v88, v88, v88 row_mirror row_mask:0xf bank_mask:0xf bound_ctrl:1
	s_nop 0
	s_nop 1
	v_add_f32_dpp v88, v88, v88 row_bcast:15 row_mask:0xa bank_mask:0xf
	s_nop 1
	v_add_f32_dpp v88, v88, v88 row_bcast:31 row_mask:0xc bank_mask:0xf
	s_nop 0
	v_readlane_b32 s26, v88, 63
	s_nop 1
	v_mov_b32_e32 v88, s26
	v_add_f32_e32 v88, 0x2b8cbccc, v88
	v_cmp_gt_f32_e32 vcc, s82, v88
	v_mul_f32_e32 v89, 0x4b800000, v88
	s_nop 0
	v_cndmask_b32_e32 v88, v88, v89, vcc
	v_rsq_f32_e32 v88, v88
	s_nop 0
	v_mul_f32_e32 v89, 0x45800000, v88
	v_cndmask_b32_e32 v88, v88, v89, vcc
	v_add_f32_e32 v89, -1.0, v91
	v_fma_f32 v89, v158, v89, 1.0
	v_mul_f32_e32 v13, v89, v13
	v_mul_f32_e32 v89, v13, v3
	v_mul_f32_e32 v93, v156, v89
	v_mul_f32_e64 v88, v92, -v88
	s_nop 0
	v_mov_b32_dpp v94, v93 quad_perm:[1,0,3,2] row_mask:0xf bank_mask:0xf
	v_fmac_f32_e32 v94, v156, v89
	s_nop 1
	v_add_f32_dpp v89, v94, v94 quad_perm:[2,3,0,1] row_mask:0xf bank_mask:0xf bound_ctrl:1
	s_nop 1
	v_add_f32_dpp v89, v89, v89 row_half_mirror row_mask:0xf bank_mask:0xf bound_ctrl:1
	s_nop 1
	v_add_f32_dpp v89, v89, v89 row_mirror row_mask:0xf bank_mask:0xf bound_ctrl:1
	s_nop 0
	s_nop 1
	v_add_f32_dpp v89, v89, v89 row_bcast:15 row_mask:0xa bank_mask:0xf
	s_nop 1
	v_add_f32_dpp v89, v89, v89 row_bcast:31 row_mask:0xc bank_mask:0xf
	s_nop 0
	v_readlane_b32 s38, v89, 63
	v_add_u32_e32 v89, s9, v1
	ds_write2st64_b32 v89, v90, v88 offset1:16
	v_mul_f32_e64 v88, v91, -v88
	ds_write2st64_b32 v89, v88, v13 offset0:32 offset1:48
	ds_write_b32 v89, v3 offset:16384
	v_add_u32_e32 v3, s8, v1
	ds_write_b32 v3, v15 offset:40960
	s_and_saveexec_b64 s[50:51], s[44:45]
	s_cbranch_execz .LBB0_401
	s_lshl_b32 s24, s96, 2
	s_add_i32 s24, s8, s24
	v_mov_b32_e32 v13, s24
	v_mov_b32_e32 v3, s38
	ds_write_b32 v13, v3 offset:45056
